# LayerNorm items take the prompt panels newest-first (panel 127 down to 0) so pre-LN rows written by the last out-proj rounds are read while still in the memory-side cache
# speedup vs baseline: 1.0110x; 1.0110x over previous
; __device__ void phaseD_handoff(const Params& p, unsigned char* smem) {
;     ...
;     if (tidd == 0) *s_item = atomicAdd(p.lnready + 2, 1);
;     __syncthreads();
;     const int it = *s_item;
;     __syncthreads();
;     if (it >= 130 * 4) break;
;     const int panel = it >> 2, chunk = it & 3;
;     if (w == 0) {
;       const int* flag = p.lnready + (panel < 128 ? 0 : 1);
;       const int need = panel < 128 ? 2048 : 16;
;       while (__hip_atomic_load(flag, __ATOMIC_RELAXED, __HIP_MEMORY_SCOPE_AGENT) < need) __builtin_amdgcn_s_sleep(8);
.LBB0_664:
	s_or_b64 exec, exec, s[4:5]
	s_waitcnt lgkmcnt(0)
	s_barrier
	ds_read_b32 v0, v65
	s_mov_b64 s[4:5], -1
	s_waitcnt lgkmcnt(0)
	s_barrier
	v_cmp_lt_i32_e32 vcc, s12, v0
	v_readfirstlane_b32 s6, v0
	s_cbranch_vccnz .LBB0_659
	s_and_b64 vcc, exec, s[2:3]
	s_ashr_i32 s4, s6, 2
	s_sub_i32 s5, 0x7f, s4
	s_cmpk_lt_i32 s4, 0x80
	s_cselect_b32 s4, s5, s4
	s_cbranch_vccnz .LBB0_670
	s_cmpk_gt_i32 s4, 0x7f
	s_cselect_b64 s[8:9], -1, 0
	v_cndmask_b32_e64 v0, 0, 1, s[8:9]
	v_lshlrev_b32_e32 v64, 2, v0
	global_load_dword v0, v64, s[50:51] sc1
	s_and_b64 s[8:9], s[8:9], exec
	s_cselect_b32 s5, 16, 0x800
	s_waitcnt vmcnt(0)
	v_cmp_le_i32_e32 vcc, s5, v0
	s_cbranch_vccnz .LBB0_669
	v_lshl_add_u64 v[0:1], s[50:51], 0, v[64:65]
